# v14epigate
# speedup vs baseline: 1.0050x; 1.0050x over previous
;     __device__ __forceinline__ void operator()(const f32x4 (&acc)[2][2][4][2], const Unit& u, int wr, int wc, int fr, int fq) const {
;         bf16_t* O_ = O; const bool gate = u.pn >= 8;
; #pragma unroll
;         for (int bj = 0; bj < 2; ++bj) { const int col = u.pn * BM + bj * HALF + wc * 32 + 8 * fq;
;             const f32x4 b0 = gate ? *(const f32x4*)(bm + col - 2048) : (f32x4){0.f, 0.f, 0.f, 0.f}, b1 = gate ? *(const f32x4*)(bm + col - 2048 + 4) : (f32x4){0.f, 0.f, 0.f, 0.f};
;             const int ocol = gate ? GATE0 + col - 2048 : col;
.LBB0_710:
	s_mov_b32 s101, 0xbfb8aa3b
	s_mov_b32 s98, 0x3b808081
	v_mov_b32_e32 v144, v199
	s_cmp_gt_i32 s88, 7
	s_cselect_b64 s[92:93], -1, 0
	s_cmp_lt_i32 s88, 8
	v_lshrrev_b32_e32 v0, 1, v144
	s_cselect_b64 s[90:91], -1, 0
	v_and_b32_e32 v0, 0x78, v0
	v_lshl_or_b32 v0, s88, 8, v0
	v_mov_b32_e32 v114, 0
	s_and_b64 vcc, exec, s[90:91]
	v_mov_b32_e32 v118, 0
	v_mov_b32_e32 v119, 0
	v_mov_b32_e32 v120, 0
	v_mov_b32_e32 v121, 0
	s_cbranch_vccnz .LBB0_712
	v_lshl_add_u64 v[116:117], v[0:1], 2, s[44:45]
	v_add_co_u32_e32 v116, vcc, 0xffffe000, v116
	s_nop 1
	v_addc_co_u32_e32 v117, vcc, -1, v117, vcc
	global_load_dwordx4 v[118:121], v[116:117], off

; __device__ __forceinline__ float sigmoidf_(float v) { return __builtin_amdgcn_rcpf(1.f + __expf(-v)); }
; __device__ __forceinline__ u32x2 gate_pack8(f32x4 v0, f32x4 v1) {
;     u32x2 w; unsigned x = 0u, y = 0u;
; #pragma unroll
;     for (int j = 0; j < 4; ++j) { x = __builtin_amdgcn_cvt_pk_u8_f32(v0[j] * 255.f, j, x); y = __builtin_amdgcn_cvt_pk_u8_f32(v1[j] * 255.f, j, y); }
;     w.x = x; w.y = y; return w;
; }
;     __device__ __forceinline__ void operator()(const f32x4 (&acc)[2][2][4][2], const Unit& u, int wr, int wc, int fr, int fq) const {
;     ...
;             const f32x4 b0 = gate ? *(const f32x4*)(bm + col - 2048) : (f32x4){0.f, 0.f, 0.f, 0.f}, b1 = gate ? *(const f32x4*)(bm + col - 2048 + 4) : (f32x4){0.f, 0.f, 0.f, 0.f};
;             const int ocol = gate ? GATE0 + col - 2048 : col;
; #pragma unroll
;             for (int ai = 0; ai < 2; ++ai)
; #pragma unroll
;                 for (int m = 0; m < 4; ++m) { const int row = u.pm * BM + ai * HALF + wr * 64 + m * 16 + fr; f32x4 v0 = acc[ai][bj][m][0] * 0.03125f, v1 = acc[ai][bj][m][1] * 0.03125f;
;                     if (gate) {
; #pragma unroll
;                         for (int j = 0; j < 4; ++j) { v0[j] = sigmoidf_(v0[j] + b0[j]); v1[j] = sigmoidf_(v1[j] + b1[j]); }
;                         *(u32x2*)((unsigned char*)(O_ + (size_t)row * NP + GATE0) + (col - 2048)) = gate_pack8(v0, v1); }
.LBB0_716:
	v_readlane_b32 s0, v253, 13
	v_readlane_b32 s1, v253, 14
	s_andn2_b64 vcc, exec, s[40:41]
	s_nop 0
	v_lshl_add_u64 v[130:131], s[0:1], 0, v[0:1]
	s_cbranch_vccnz .LBB0_718
	s_waitcnt vmcnt(0)
	v_mul_f32_e32 v114, s101, v114
	v_mul_f32_e32 v115, s101, v115
	v_mul_f32_e32 v116, s101, v116
	v_mul_f32_e32 v117, s101, v117
	v_mul_f32_e32 v118, s101, v118
	v_mul_f32_e32 v119, s101, v119
	v_mul_f32_e32 v120, s101, v120
	v_mul_f32_e32 v121, s101, v121
	v_fma_f32 v134, v134, s101, v118
	v_fma_f32 v146, v146, s101, v114
	v_fma_f32 v135, v135, s101, v119
	v_exp_f32_e32 v134, v134
	v_fma_f32 v147, v147, s101, v115
	v_exp_f32_e32 v146, v146
	v_exp_f32_e32 v135, v135
	v_fma_f32 v136, v136, s101, v120
	v_fma_f32 v132, v132, s101, v116
	v_exp_f32_e32 v147, v147
	v_fma_f32 v137, v137, s101, v121
	v_fma_f32 v133, v133, s101, v117
	v_exp_f32_e32 v136, v136
	v_exp_f32_e32 v132, v132
	v_fma_f32 v134, v134, s98, s98
	v_exp_f32_e32 v137, v137
	v_exp_f32_e32 v133, v133
	v_rcp_f32_e32 v134, v134
	v_fma_f32 v146, v146, s98, s98
	v_fma_f32 v135, v135, s98, s98
	v_rcp_f32_e32 v146, v146
	v_rcp_f32_e32 v135, v135
	v_fma_f32 v147, v147, s98, s98
	v_rcp_f32_e32 v147, v147
	v_fma_f32 v136, v136, s98, s98
	v_fma_f32 v132, v132, s98, s98
	v_rcp_f32_e32 v136, v136
	v_rcp_f32_e32 v132, v132
	v_fma_f32 v137, v137, s98, s98
	v_fma_f32 v133, v133, s98, s98
	v_rcp_f32_e32 v137, v137
	v_rcp_f32_e32 v133, v133
	v_cvt_pk_u8_f32 v134, v134, 0, 0
	v_cvt_pk_u8_f32 v146, v146, 0, 0
	v_cvt_pk_u8_f32 v134, v135, 1, v134
	v_cvt_pk_u8_f32 v135, v147, 1, v146
	v_cvt_pk_u8_f32 v134, v136, 2, v134
	v_cvt_pk_u8_f32 v135, v132, 2, v135
	v_cvt_pk_u8_f32 v132, v137, 3, v134
	v_cvt_pk_u8_f32 v133, v133, 3, v135
	v_mad_i64_i32 v[134:135], s[0:1], v150, s31, v[130:131]
	v_add_co_u32_e32 v134, vcc, 0x3000, v134
	s_nop 1
	v_addc_co_u32_e32 v135, vcc, 0, v135, vcc
	flat_store_dwordx2 v[134:135], v[132:133] offset:512

; __device__ __forceinline__ float sigmoidf_(float v) { return __builtin_amdgcn_rcpf(1.f + __expf(-v)); }
; __device__ __forceinline__ u32x2 gate_pack8(f32x4 v0, f32x4 v1) {
;     u32x2 w; unsigned x = 0u, y = 0u;
; #pragma unroll
;     for (int j = 0; j < 4; ++j) { x = __builtin_amdgcn_cvt_pk_u8_f32(v0[j] * 255.f, j, x); y = __builtin_amdgcn_cvt_pk_u8_f32(v1[j] * 255.f, j, y); }
;     w.x = x; w.y = y; return w;
; }
;     __device__ __forceinline__ void operator()(const f32x4 (&acc)[2][2][4][2], const Unit& u, int wr, int wc, int fr, int fq) const {
;     ...
;                 for (int m = 0; m < 4; ++m) { const int row = u.pm * BM + ai * HALF + wr * 64 + m * 16 + fr; f32x4 v0 = acc[ai][bj][m][0] * 0.03125f, v1 = acc[ai][bj][m][1] * 0.03125f;
;                     if (gate) {
; #pragma unroll
;                         for (int j = 0; j < 4; ++j) { v0[j] = sigmoidf_(v0[j] + b0[j]); v1[j] = sigmoidf_(v1[j] + b1[j]); }
;                         *(u32x2*)((unsigned char*)(O_ + (size_t)row * NP + GATE0) + (col - 2048)) = gate_pack8(v0, v1); }
.LBB0_720:
	s_andn2_b64 vcc, exec, s[88:89]
	s_cbranch_vccnz .LBB0_722
	s_waitcnt vmcnt(0)
	v_fma_f32 v126, v126, s101, v118
	v_fma_f32 v122, v122, s101, v114
	v_fma_f32 v127, v127, s101, v119
	v_fma_f32 v123, v123, s101, v115
	v_exp_f32_e32 v126, v126
	v_exp_f32_e32 v122, v122
	v_fma_f32 v128, v128, s101, v120
	v_fma_f32 v124, v124, s101, v116
	v_exp_f32_e32 v127, v127
	v_exp_f32_e32 v123, v123
	v_fma_f32 v129, v129, s101, v121
	v_exp_f32_e32 v128, v128
	v_exp_f32_e32 v124, v124
	v_fma_f32 v125, v125, s101, v117
	v_exp_f32_e32 v129, v129
	v_fma_f32 v126, v126, s98, s98
	v_fma_f32 v122, v122, s98, s98
	v_exp_f32_e32 v125, v125
	v_rcp_f32_e32 v126, v126
	v_rcp_f32_e32 v122, v122
	v_fma_f32 v127, v127, s98, s98
	v_fma_f32 v123, v123, s98, s98
	v_rcp_f32_e32 v127, v127
	v_rcp_f32_e32 v123, v123
	v_fma_f32 v128, v128, s98, s98
	v_fma_f32 v124, v124, s98, s98
	v_rcp_f32_e32 v128, v128
	v_rcp_f32_e32 v124, v124
	v_fma_f32 v129, v129, s98, s98
	v_rcp_f32_e32 v129, v129
	v_fma_f32 v125, v125, s98, s98
	v_rcp_f32_e32 v125, v125
	v_cvt_pk_u8_f32 v126, v126, 0, 0
	v_cvt_pk_u8_f32 v122, v122, 0, 0
	v_cvt_pk_u8_f32 v126, v127, 1, v126
	v_cvt_pk_u8_f32 v122, v123, 1, v122
	v_cvt_pk_u8_f32 v123, v128, 2, v126
	v_cvt_pk_u8_f32 v124, v124, 2, v122
	v_cvt_pk_u8_f32 v122, v129, 3, v123
	v_cvt_pk_u8_f32 v123, v125, 3, v124
	v_mad_i64_i32 v[124:125], s[0:1], v132, s31, v[130:131]
	v_add_co_u32_e32 v124, vcc, 0x3000, v124
	s_nop 1
	v_addc_co_u32_e32 v125, vcc, 0, v125, vcc
	flat_store_dwordx2 v[124:125], v[122:123] offset:512

; __device__ __forceinline__ float sigmoidf_(float v) { return __builtin_amdgcn_rcpf(1.f + __expf(-v)); }
; __device__ __forceinline__ u32x2 gate_pack8(f32x4 v0, f32x4 v1) {
;     u32x2 w; unsigned x = 0u, y = 0u;
; #pragma unroll
;     for (int j = 0; j < 4; ++j) { x = __builtin_amdgcn_cvt_pk_u8_f32(v0[j] * 255.f, j, x); y = __builtin_amdgcn_cvt_pk_u8_f32(v1[j] * 255.f, j, y); }
;     w.x = x; w.y = y; return w;
; }
;     __device__ __forceinline__ void operator()(const f32x4 (&acc)[2][2][4][2], const Unit& u, int wr, int wc, int fr, int fq) const {
;     ...
;                 for (int m = 0; m < 4; ++m) { const int row = u.pm * BM + ai * HALF + wr * 64 + m * 16 + fr; f32x4 v0 = acc[ai][bj][m][0] * 0.03125f, v1 = acc[ai][bj][m][1] * 0.03125f;
;                     if (gate) {
; #pragma unroll
;                         for (int j = 0; j < 4; ++j) { v0[j] = sigmoidf_(v0[j] + b0[j]); v1[j] = sigmoidf_(v1[j] + b1[j]); }
;                         *(u32x2*)((unsigned char*)(O_ + (size_t)row * NP + GATE0) + (col - 2048)) = gate_pack8(v0, v1); }
.LBB0_724:
	s_andn2_b64 vcc, exec, s[88:89]
	s_cbranch_vccnz .LBB0_726
	s_waitcnt vmcnt(0)
	v_fma_f32 v110, v110, s101, v118
	v_fma_f32 v106, v106, s101, v114
	v_fma_f32 v111, v111, s101, v119
	v_fma_f32 v107, v107, s101, v115
	v_exp_f32_e32 v110, v110
	v_exp_f32_e32 v106, v106
	v_fma_f32 v112, v112, s101, v120
	v_fma_f32 v108, v108, s101, v116
	v_exp_f32_e32 v111, v111
	v_exp_f32_e32 v107, v107
	v_fma_f32 v113, v113, s101, v121
	v_exp_f32_e32 v112, v112
	v_exp_f32_e32 v108, v108
	v_fma_f32 v109, v109, s101, v117
	v_exp_f32_e32 v113, v113
	v_fma_f32 v110, v110, s98, s98
	v_fma_f32 v106, v106, s98, s98
	v_exp_f32_e32 v109, v109
	v_rcp_f32_e32 v110, v110
	v_rcp_f32_e32 v106, v106
	v_fma_f32 v111, v111, s98, s98
	v_fma_f32 v107, v107, s98, s98
	v_rcp_f32_e32 v111, v111
	v_rcp_f32_e32 v107, v107
	v_fma_f32 v112, v112, s98, s98
	v_fma_f32 v108, v108, s98, s98
	v_rcp_f32_e32 v112, v112
	v_rcp_f32_e32 v108, v108
	v_fma_f32 v113, v113, s98, s98
	v_rcp_f32_e32 v113, v113
	v_fma_f32 v109, v109, s98, s98
	v_rcp_f32_e32 v109, v109
	v_cvt_pk_u8_f32 v110, v110, 0, 0
	v_cvt_pk_u8_f32 v106, v106, 0, 0
	v_cvt_pk_u8_f32 v110, v111, 1, v110
	v_cvt_pk_u8_f32 v106, v107, 1, v106
	v_cvt_pk_u8_f32 v107, v112, 2, v110
	v_cvt_pk_u8_f32 v108, v108, 2, v106
	v_cvt_pk_u8_f32 v106, v113, 3, v107
	v_cvt_pk_u8_f32 v107, v109, 3, v108
	v_mad_i64_i32 v[108:109], s[0:1], v122, s31, v[130:131]
	v_add_co_u32_e32 v108, vcc, 0x3000, v108
	s_nop 1
	v_addc_co_u32_e32 v109, vcc, 0, v109, vcc
	flat_store_dwordx2 v[108:109], v[106:107] offset:512

; __device__ __forceinline__ float sigmoidf_(float v) { return __builtin_amdgcn_rcpf(1.f + __expf(-v)); }
; __device__ __forceinline__ u32x2 gate_pack8(f32x4 v0, f32x4 v1) {
;     u32x2 w; unsigned x = 0u, y = 0u;
; #pragma unroll
;     for (int j = 0; j < 4; ++j) { x = __builtin_amdgcn_cvt_pk_u8_f32(v0[j] * 255.f, j, x); y = __builtin_amdgcn_cvt_pk_u8_f32(v1[j] * 255.f, j, y); }
;     w.x = x; w.y = y; return w;
; }
;     __device__ __forceinline__ void operator()(const f32x4 (&acc)[2][2][4][2], const Unit& u, int wr, int wc, int fr, int fq) const {
;     ...
;                 for (int m = 0; m < 4; ++m) { const int row = u.pm * BM + ai * HALF + wr * 64 + m * 16 + fr; f32x4 v0 = acc[ai][bj][m][0] * 0.03125f, v1 = acc[ai][bj][m][1] * 0.03125f;
;                     if (gate) {
; #pragma unroll
;                         for (int j = 0; j < 4; ++j) { v0[j] = sigmoidf_(v0[j] + b0[j]); v1[j] = sigmoidf_(v1[j] + b1[j]); }
;                         *(u32x2*)((unsigned char*)(O_ + (size_t)row * NP + GATE0) + (col - 2048)) = gate_pack8(v0, v1); }
.LBB0_728:
	s_andn2_b64 vcc, exec, s[88:89]
	s_cbranch_vccnz .LBB0_730
	s_waitcnt vmcnt(0)
	v_fma_f32 v102, v102, s101, v118
	v_fma_f32 v98, v98, s101, v114
	v_fma_f32 v103, v103, s101, v119
	v_fma_f32 v99, v99, s101, v115
	v_exp_f32_e32 v102, v102
	v_exp_f32_e32 v98, v98
	v_fma_f32 v104, v104, s101, v120
	v_fma_f32 v100, v100, s101, v116
	v_exp_f32_e32 v103, v103
	v_exp_f32_e32 v99, v99
	v_fma_f32 v105, v105, s101, v121
	v_exp_f32_e32 v104, v104
	v_exp_f32_e32 v100, v100
	v_fma_f32 v101, v101, s101, v117
	v_exp_f32_e32 v105, v105
	v_fma_f32 v102, v102, s98, s98
	v_fma_f32 v98, v98, s98, s98
	v_exp_f32_e32 v101, v101
	v_rcp_f32_e32 v102, v102
	v_rcp_f32_e32 v98, v98
	v_fma_f32 v103, v103, s98, s98
	v_fma_f32 v99, v99, s98, s98
	v_rcp_f32_e32 v103, v103
	v_rcp_f32_e32 v99, v99
	v_fma_f32 v104, v104, s98, s98
	v_fma_f32 v100, v100, s98, s98
	v_rcp_f32_e32 v104, v104
	v_rcp_f32_e32 v100, v100
	v_fma_f32 v105, v105, s98, s98
	v_rcp_f32_e32 v105, v105
	v_fma_f32 v101, v101, s98, s98
	v_rcp_f32_e32 v101, v101
	v_cvt_pk_u8_f32 v102, v102, 0, 0
	v_cvt_pk_u8_f32 v98, v98, 0, 0
	v_cvt_pk_u8_f32 v102, v103, 1, v102
	v_cvt_pk_u8_f32 v98, v99, 1, v98
	v_cvt_pk_u8_f32 v99, v104, 2, v102
	v_cvt_pk_u8_f32 v100, v100, 2, v98
	v_cvt_pk_u8_f32 v98, v105, 3, v99
	v_cvt_pk_u8_f32 v99, v101, 3, v100
	v_mad_i64_i32 v[100:101], s[0:1], v106, s31, v[130:131]
	v_add_co_u32_e32 v100, vcc, 0x3000, v100
	s_nop 1
	v_addc_co_u32_e32 v101, vcc, 0, v101, vcc
	flat_store_dwordx2 v[100:101], v[98:99] offset:512

; __device__ __forceinline__ float sigmoidf_(float v) { return __builtin_amdgcn_rcpf(1.f + __expf(-v)); }
; __device__ __forceinline__ u32x2 gate_pack8(f32x4 v0, f32x4 v1) {
;     u32x2 w; unsigned x = 0u, y = 0u;
; #pragma unroll
;     for (int j = 0; j < 4; ++j) { x = __builtin_amdgcn_cvt_pk_u8_f32(v0[j] * 255.f, j, x); y = __builtin_amdgcn_cvt_pk_u8_f32(v1[j] * 255.f, j, y); }
;     w.x = x; w.y = y; return w;
; }
;     __device__ __forceinline__ void operator()(const f32x4 (&acc)[2][2][4][2], const Unit& u, int wr, int wc, int fr, int fq) const {
;     ...
;                 for (int m = 0; m < 4; ++m) { const int row = u.pm * BM + ai * HALF + wr * 64 + m * 16 + fr; f32x4 v0 = acc[ai][bj][m][0] * 0.03125f, v1 = acc[ai][bj][m][1] * 0.03125f;
;                     if (gate) {
; #pragma unroll
;                         for (int j = 0; j < 4; ++j) { v0[j] = sigmoidf_(v0[j] + b0[j]); v1[j] = sigmoidf_(v1[j] + b1[j]); }
;                         *(u32x2*)((unsigned char*)(O_ + (size_t)row * NP + GATE0) + (col - 2048)) = gate_pack8(v0, v1); }
.LBB0_732:
	s_andn2_b64 vcc, exec, s[88:89]
	s_cbranch_vccnz .LBB0_734
	s_waitcnt vmcnt(0)
	v_fma_f32 v94, v94, s101, v118
	v_fma_f32 v90, v90, s101, v114
	v_fma_f32 v95, v95, s101, v119
	v_fma_f32 v91, v91, s101, v115
	v_exp_f32_e32 v94, v94
	v_exp_f32_e32 v90, v90
	v_fma_f32 v96, v96, s101, v120
	v_fma_f32 v92, v92, s101, v116
	v_exp_f32_e32 v95, v95
	v_exp_f32_e32 v91, v91
	v_fma_f32 v97, v97, s101, v121
	v_exp_f32_e32 v96, v96
	v_exp_f32_e32 v92, v92
	v_fma_f32 v93, v93, s101, v117
	v_exp_f32_e32 v97, v97
	v_fma_f32 v94, v94, s98, s98
	v_fma_f32 v90, v90, s98, s98
	v_exp_f32_e32 v93, v93
	v_rcp_f32_e32 v94, v94
	v_rcp_f32_e32 v90, v90
	v_fma_f32 v95, v95, s98, s98
	v_fma_f32 v91, v91, s98, s98
	v_rcp_f32_e32 v95, v95
	v_rcp_f32_e32 v91, v91
	v_fma_f32 v96, v96, s98, s98
	v_fma_f32 v92, v92, s98, s98
	v_rcp_f32_e32 v96, v96
	v_rcp_f32_e32 v92, v92
	v_fma_f32 v97, v97, s98, s98
	v_rcp_f32_e32 v97, v97
	v_fma_f32 v93, v93, s98, s98
	v_rcp_f32_e32 v93, v93
	v_cvt_pk_u8_f32 v94, v94, 0, 0
	v_cvt_pk_u8_f32 v90, v90, 0, 0
	v_cvt_pk_u8_f32 v94, v95, 1, v94
	v_cvt_pk_u8_f32 v90, v91, 1, v90
	v_cvt_pk_u8_f32 v91, v96, 2, v94
	v_cvt_pk_u8_f32 v92, v92, 2, v90
	v_cvt_pk_u8_f32 v90, v97, 3, v91
	v_cvt_pk_u8_f32 v91, v93, 3, v92
	v_mad_i64_i32 v[92:93], s[0:1], v98, s31, v[130:131]
	v_add_co_u32_e32 v92, vcc, 0x3000, v92
	s_nop 1
	v_addc_co_u32_e32 v93, vcc, 0, v93, vcc
	flat_store_dwordx2 v[92:93], v[90:91] offset:512

; __device__ __forceinline__ float sigmoidf_(float v) { return __builtin_amdgcn_rcpf(1.f + __expf(-v)); }
; __device__ __forceinline__ u32x2 gate_pack8(f32x4 v0, f32x4 v1) {
;     u32x2 w; unsigned x = 0u, y = 0u;
; #pragma unroll
;     for (int j = 0; j < 4; ++j) { x = __builtin_amdgcn_cvt_pk_u8_f32(v0[j] * 255.f, j, x); y = __builtin_amdgcn_cvt_pk_u8_f32(v1[j] * 255.f, j, y); }
;     w.x = x; w.y = y; return w;
; }
;     __device__ __forceinline__ void operator()(const f32x4 (&acc)[2][2][4][2], const Unit& u, int wr, int wc, int fr, int fq) const {
;     ...
;                 for (int m = 0; m < 4; ++m) { const int row = u.pm * BM + ai * HALF + wr * 64 + m * 16 + fr; f32x4 v0 = acc[ai][bj][m][0] * 0.03125f, v1 = acc[ai][bj][m][1] * 0.03125f;
;                     if (gate) {
; #pragma unroll
;                         for (int j = 0; j < 4; ++j) { v0[j] = sigmoidf_(v0[j] + b0[j]); v1[j] = sigmoidf_(v1[j] + b1[j]); }
;                         *(u32x2*)((unsigned char*)(O_ + (size_t)row * NP + GATE0) + (col - 2048)) = gate_pack8(v0, v1); }
.LBB0_736:
	s_andn2_b64 vcc, exec, s[88:89]
	s_cbranch_vccnz .LBB0_738
	s_waitcnt vmcnt(0)
	v_fma_f32 v86, v86, s101, v118
	v_fma_f32 v82, v82, s101, v114
	v_fma_f32 v87, v87, s101, v119
	v_fma_f32 v83, v83, s101, v115
	v_exp_f32_e32 v86, v86
	v_exp_f32_e32 v82, v82
	v_fma_f32 v88, v88, s101, v120
	v_fma_f32 v84, v84, s101, v116
	v_exp_f32_e32 v87, v87
	v_exp_f32_e32 v83, v83
	v_fma_f32 v89, v89, s101, v121
	v_exp_f32_e32 v88, v88
	v_exp_f32_e32 v84, v84
	v_fma_f32 v85, v85, s101, v117
	v_exp_f32_e32 v89, v89
	v_fma_f32 v86, v86, s98, s98
	v_fma_f32 v82, v82, s98, s98
	v_exp_f32_e32 v85, v85
	v_rcp_f32_e32 v86, v86
	v_rcp_f32_e32 v82, v82
	v_fma_f32 v87, v87, s98, s98
	v_fma_f32 v83, v83, s98, s98
	v_rcp_f32_e32 v87, v87
	v_rcp_f32_e32 v83, v83
	v_fma_f32 v88, v88, s98, s98
	v_fma_f32 v84, v84, s98, s98
	v_rcp_f32_e32 v88, v88
	v_rcp_f32_e32 v84, v84
	v_fma_f32 v89, v89, s98, s98
	v_rcp_f32_e32 v89, v89
	v_fma_f32 v85, v85, s98, s98
	v_rcp_f32_e32 v85, v85
	v_cvt_pk_u8_f32 v86, v86, 0, 0
	v_cvt_pk_u8_f32 v82, v82, 0, 0
	v_cvt_pk_u8_f32 v86, v87, 1, v86
	v_cvt_pk_u8_f32 v82, v83, 1, v82
	v_cvt_pk_u8_f32 v83, v88, 2, v86
	v_cvt_pk_u8_f32 v84, v84, 2, v82
	v_cvt_pk_u8_f32 v82, v89, 3, v83
	v_cvt_pk_u8_f32 v83, v85, 3, v84
	v_mad_i64_i32 v[84:85], s[0:1], v90, s31, v[130:131]
	v_add_co_u32_e32 v84, vcc, 0x3000, v84
	s_nop 1
	v_addc_co_u32_e32 v85, vcc, 0, v85, vcc
	flat_store_dwordx2 v[84:85], v[82:83] offset:512

; __device__ __forceinline__ float sigmoidf_(float v) { return __builtin_amdgcn_rcpf(1.f + __expf(-v)); }
; __device__ __forceinline__ u32x2 gate_pack8(f32x4 v0, f32x4 v1) {
;     u32x2 w; unsigned x = 0u, y = 0u;
; #pragma unroll
;     for (int j = 0; j < 4; ++j) { x = __builtin_amdgcn_cvt_pk_u8_f32(v0[j] * 255.f, j, x); y = __builtin_amdgcn_cvt_pk_u8_f32(v1[j] * 255.f, j, y); }
;     w.x = x; w.y = y; return w;
; }
;     __device__ __forceinline__ void operator()(const f32x4 (&acc)[2][2][4][2], const Unit& u, int wr, int wc, int fr, int fq) const {
;     ...
;                 for (int m = 0; m < 4; ++m) { const int row = u.pm * BM + ai * HALF + wr * 64 + m * 16 + fr; f32x4 v0 = acc[ai][bj][m][0] * 0.03125f, v1 = acc[ai][bj][m][1] * 0.03125f;
;                     if (gate) {
; #pragma unroll
;                         for (int j = 0; j < 4; ++j) { v0[j] = sigmoidf_(v0[j] + b0[j]); v1[j] = sigmoidf_(v1[j] + b1[j]); }
;                         *(u32x2*)((unsigned char*)(O_ + (size_t)row * NP + GATE0) + (col - 2048)) = gate_pack8(v0, v1); }
.LBB0_740:
	s_andn2_b64 vcc, exec, s[88:89]
	s_cbranch_vccnz .LBB0_742
	s_waitcnt vmcnt(0)
	v_fma_f32 v78, v78, s101, v118
	v_fma_f32 v74, v74, s101, v114
	v_fma_f32 v79, v79, s101, v119
	v_fma_f32 v75, v75, s101, v115
	v_exp_f32_e32 v78, v78
	v_exp_f32_e32 v74, v74
	v_fma_f32 v80, v80, s101, v120
	v_fma_f32 v76, v76, s101, v116
	v_exp_f32_e32 v79, v79
	v_exp_f32_e32 v75, v75
	v_fma_f32 v81, v81, s101, v121
	v_exp_f32_e32 v80, v80
	v_exp_f32_e32 v76, v76
	v_fma_f32 v77, v77, s101, v117
	v_exp_f32_e32 v81, v81
	v_fma_f32 v78, v78, s98, s98
	v_fma_f32 v74, v74, s98, s98
	v_exp_f32_e32 v77, v77
	v_rcp_f32_e32 v78, v78
	v_rcp_f32_e32 v74, v74
	v_fma_f32 v79, v79, s98, s98
	v_fma_f32 v75, v75, s98, s98
	v_rcp_f32_e32 v79, v79
	v_rcp_f32_e32 v75, v75
	v_fma_f32 v80, v80, s98, s98
	v_fma_f32 v76, v76, s98, s98
	v_rcp_f32_e32 v80, v80
	v_rcp_f32_e32 v76, v76
	v_fma_f32 v81, v81, s98, s98
	v_rcp_f32_e32 v81, v81
	v_fma_f32 v77, v77, s98, s98
	v_rcp_f32_e32 v77, v77
	v_cvt_pk_u8_f32 v78, v78, 0, 0
	v_cvt_pk_u8_f32 v74, v74, 0, 0
	v_cvt_pk_u8_f32 v78, v79, 1, v78
	v_cvt_pk_u8_f32 v74, v75, 1, v74
	v_cvt_pk_u8_f32 v75, v80, 2, v78
	v_cvt_pk_u8_f32 v76, v76, 2, v74
	v_cvt_pk_u8_f32 v74, v81, 3, v75
	v_cvt_pk_u8_f32 v75, v77, 3, v76
	v_mad_i64_i32 v[76:77], s[0:1], v82, s31, v[130:131]
	v_add_co_u32_e32 v76, vcc, 0x3000, v76
	s_nop 1
	v_addc_co_u32_e32 v77, vcc, 0, v77, vcc
	flat_store_dwordx2 v[76:77], v[74:75] offset:512

; __device__ __forceinline__ float sigmoidf_(float v) { return __builtin_amdgcn_rcpf(1.f + __expf(-v)); }
; __device__ __forceinline__ u32x2 gate_pack8(f32x4 v0, f32x4 v1) {
;     u32x2 w; unsigned x = 0u, y = 0u;
; #pragma unroll
;     for (int j = 0; j < 4; ++j) { x = __builtin_amdgcn_cvt_pk_u8_f32(v0[j] * 255.f, j, x); y = __builtin_amdgcn_cvt_pk_u8_f32(v1[j] * 255.f, j, y); }
;     w.x = x; w.y = y; return w;
; }
;     __device__ __forceinline__ void operator()(const f32x4 (&acc)[2][2][4][2], const Unit& u, int wr, int wc, int fr, int fq) const {
;     ...
;                 for (int m = 0; m < 4; ++m) { const int row = u.pm * BM + ai * HALF + wr * 64 + m * 16 + fr; f32x4 v0 = acc[ai][bj][m][0] * 0.03125f, v1 = acc[ai][bj][m][1] * 0.03125f;
;                     if (gate) {
; #pragma unroll
;                         for (int j = 0; j < 4; ++j) { v0[j] = sigmoidf_(v0[j] + b0[j]); v1[j] = sigmoidf_(v1[j] + b1[j]); }
;                         *(u32x2*)((unsigned char*)(O_ + (size_t)row * NP + GATE0) + (col - 2048)) = gate_pack8(v0, v1); }
.LBB0_744:
	s_andn2_b64 vcc, exec, s[88:89]
	s_cbranch_vccnz .LBB0_746
	s_waitcnt vmcnt(0)
	v_fma_f32 v70, v70, s101, v118
	v_fma_f32 v66, v66, s101, v114
	v_fma_f32 v71, v71, s101, v119
	v_fma_f32 v67, v67, s101, v115
	v_exp_f32_e32 v70, v70
	v_exp_f32_e32 v66, v66
	v_fma_f32 v72, v72, s101, v120
	v_fma_f32 v68, v68, s101, v116
	v_exp_f32_e32 v71, v71
	v_exp_f32_e32 v67, v67
	v_fma_f32 v73, v73, s101, v121
	v_exp_f32_e32 v72, v72
	v_exp_f32_e32 v68, v68
	v_fma_f32 v69, v69, s101, v117
	v_exp_f32_e32 v73, v73
	v_fma_f32 v70, v70, s98, s98
	v_fma_f32 v66, v66, s98, s98
	v_exp_f32_e32 v69, v69
	v_rcp_f32_e32 v70, v70
	v_rcp_f32_e32 v66, v66
	v_fma_f32 v71, v71, s98, s98
	v_fma_f32 v67, v67, s98, s98
	v_rcp_f32_e32 v71, v71
	v_rcp_f32_e32 v67, v67
	v_fma_f32 v72, v72, s98, s98
	v_fma_f32 v68, v68, s98, s98
	v_rcp_f32_e32 v72, v72
	v_rcp_f32_e32 v68, v68
	v_fma_f32 v73, v73, s98, s98
	v_rcp_f32_e32 v73, v73
	v_fma_f32 v69, v69, s98, s98
	v_rcp_f32_e32 v69, v69
	v_cvt_pk_u8_f32 v70, v70, 0, 0
	v_cvt_pk_u8_f32 v66, v66, 0, 0
	v_cvt_pk_u8_f32 v70, v71, 1, v70
	v_cvt_pk_u8_f32 v66, v67, 1, v66
	v_cvt_pk_u8_f32 v67, v72, 2, v70
	v_cvt_pk_u8_f32 v68, v68, 2, v66
	v_cvt_pk_u8_f32 v66, v73, 3, v67
	v_cvt_pk_u8_f32 v67, v69, 3, v68
	v_mad_i64_i32 v[68:69], s[0:1], v76, s31, v[130:131]
	v_add_co_u32_e32 v68, vcc, 0x3000, v68
	s_nop 1
	v_addc_co_u32_e32 v69, vcc, 0, v69, vcc
	flat_store_dwordx2 v[68:69], v[66:67] offset:512

; __device__ __forceinline__ float sigmoidf_(float v) { return __builtin_amdgcn_rcpf(1.f + __expf(-v)); }
; __device__ __forceinline__ u32x2 gate_pack8(f32x4 v0, f32x4 v1) {
;     u32x2 w; unsigned x = 0u, y = 0u;
; #pragma unroll
;     for (int j = 0; j < 4; ++j) { x = __builtin_amdgcn_cvt_pk_u8_f32(v0[j] * 255.f, j, x); y = __builtin_amdgcn_cvt_pk_u8_f32(v1[j] * 255.f, j, y); }
;     w.x = x; w.y = y; return w;
; }
;     __device__ __forceinline__ void operator()(const f32x4 (&acc)[2][2][4][2], const Unit& u, int wr, int wc, int fr, int fq) const {
;     ...
;             const f32x4 b0 = gate ? *(const f32x4*)(bm + col - 2048) : (f32x4){0.f, 0.f, 0.f, 0.f}, b1 = gate ? *(const f32x4*)(bm + col - 2048 + 4) : (f32x4){0.f, 0.f, 0.f, 0.f};
;             const int ocol = gate ? GATE0 + col - 2048 : col;
; #pragma unroll
;             for (int ai = 0; ai < 2; ++ai)
; #pragma unroll
;                 for (int m = 0; m < 4; ++m) { const int row = u.pm * BM + ai * HALF + wr * 64 + m * 16 + fr; f32x4 v0 = acc[ai][bj][m][0] * 0.03125f, v1 = acc[ai][bj][m][1] * 0.03125f;
;                     if (gate) {
; #pragma unroll
;                         for (int j = 0; j < 4; ++j) { v0[j] = sigmoidf_(v0[j] + b0[j]); v1[j] = sigmoidf_(v1[j] + b1[j]); }
;                         *(u32x2*)((unsigned char*)(O_ + (size_t)row * NP + GATE0) + (col - 2048)) = gate_pack8(v0, v1); }
.LBB0_752:
	s_andn2_b64 vcc, exec, s[42:43]
	v_mov_b32_e32 v0, v74
	s_cbranch_vccnz .LBB0_754
	s_waitcnt vmcnt(0)
	v_mul_f32_e32 v66, s101, v66
	v_mul_f32_e32 v67, s101, v67
	v_mul_f32_e32 v68, s101, v68
	v_mul_f32_e32 v69, s101, v69
	v_mul_f32_e32 v70, s101, v70
	v_mul_f32_e32 v71, s101, v71
	v_mul_f32_e32 v72, s101, v72
	v_mul_f32_e32 v73, s101, v73
	v_fma_f32 v62, v62, s101, v70
	v_fma_f32 v58, v58, s101, v66
	v_fma_f32 v63, v63, s101, v71
	v_fma_f32 v59, v59, s101, v67
	v_exp_f32_e32 v62, v62
	v_exp_f32_e32 v58, v58
	v_fma_f32 v64, v64, s101, v72
	v_fma_f32 v60, v60, s101, v68
	v_exp_f32_e32 v63, v63
	v_exp_f32_e32 v59, v59
	v_fma_f32 v65, v65, s101, v73
	v_exp_f32_e32 v64, v64
	v_exp_f32_e32 v60, v60
	v_fma_f32 v61, v61, s101, v69
	v_exp_f32_e32 v65, v65
	v_fma_f32 v62, v62, s98, s98
	v_fma_f32 v58, v58, s98, s98
	v_exp_f32_e32 v61, v61
	v_rcp_f32_e32 v62, v62
	v_rcp_f32_e32 v58, v58
	v_fma_f32 v63, v63, s98, s98
	v_fma_f32 v59, v59, s98, s98
	v_rcp_f32_e32 v63, v63
	v_rcp_f32_e32 v59, v59
	v_fma_f32 v64, v64, s98, s98
	v_fma_f32 v60, v60, s98, s98
	v_rcp_f32_e32 v64, v64
	v_rcp_f32_e32 v60, v60
	v_fma_f32 v65, v65, s98, s98
	v_rcp_f32_e32 v65, v65
	v_fma_f32 v61, v61, s98, s98
	v_rcp_f32_e32 v61, v61
	v_cvt_pk_u8_f32 v62, v62, 0, 0
	v_cvt_pk_u8_f32 v58, v58, 0, 0
	v_cvt_pk_u8_f32 v62, v63, 1, v62
	v_cvt_pk_u8_f32 v58, v59, 1, v58
	v_cvt_pk_u8_f32 v59, v64, 2, v62
	v_cvt_pk_u8_f32 v60, v60, 2, v58
	v_readlane_b32 s0, v253, 13
	v_cvt_pk_u8_f32 v58, v65, 3, v59
	v_readlane_b32 s1, v253, 14
	v_cvt_pk_u8_f32 v59, v61, 3, v60
	s_nop 0
	v_mov_b64_e32 v[60:61], s[0:1]
	v_mad_i64_i32 v[60:61], s[0:1], v150, s31, v[60:61]
	v_lshl_add_u64 v[60:61], v[60:61], 0, v[0:1]
	v_add_co_u32_e32 v60, vcc, 0x3000, v60
	s_nop 1
	v_addc_co_u32_e32 v61, vcc, 0, v61, vcc
	flat_store_dwordx2 v[60:61], v[58:59] offset:512

; __device__ __forceinline__ float sigmoidf_(float v) { return __builtin_amdgcn_rcpf(1.f + __expf(-v)); }
; __device__ __forceinline__ u32x2 gate_pack8(f32x4 v0, f32x4 v1) {
;     u32x2 w; unsigned x = 0u, y = 0u;
; #pragma unroll
;     for (int j = 0; j < 4; ++j) { x = __builtin_amdgcn_cvt_pk_u8_f32(v0[j] * 255.f, j, x); y = __builtin_amdgcn_cvt_pk_u8_f32(v1[j] * 255.f, j, y); }
;     w.x = x; w.y = y; return w;
; }
;     __device__ __forceinline__ void operator()(const f32x4 (&acc)[2][2][4][2], const Unit& u, int wr, int wc, int fr, int fq) const {
;     ...
;                 for (int m = 0; m < 4; ++m) { const int row = u.pm * BM + ai * HALF + wr * 64 + m * 16 + fr; f32x4 v0 = acc[ai][bj][m][0] * 0.03125f, v1 = acc[ai][bj][m][1] * 0.03125f;
;                     if (gate) {
; #pragma unroll
;                         for (int j = 0; j < 4; ++j) { v0[j] = sigmoidf_(v0[j] + b0[j]); v1[j] = sigmoidf_(v1[j] + b1[j]); }
;                         *(u32x2*)((unsigned char*)(O_ + (size_t)row * NP + GATE0) + (col - 2048)) = gate_pack8(v0, v1); }
.LBB0_756:
	s_andn2_b64 vcc, exec, s[42:43]
	s_cbranch_vccnz .LBB0_758
	s_waitcnt vmcnt(0)
	v_fma_f32 v54, v54, s101, v70
	v_fma_f32 v50, v50, s101, v66
	v_fma_f32 v55, v55, s101, v71
	v_fma_f32 v51, v51, s101, v67
	v_exp_f32_e32 v54, v54
	v_exp_f32_e32 v50, v50
	v_fma_f32 v56, v56, s101, v72
	v_fma_f32 v52, v52, s101, v68
	v_exp_f32_e32 v55, v55
	v_exp_f32_e32 v51, v51
	v_fma_f32 v57, v57, s101, v73
	v_exp_f32_e32 v56, v56
	v_exp_f32_e32 v52, v52
	v_fma_f32 v53, v53, s101, v69
	v_exp_f32_e32 v57, v57
	v_fma_f32 v54, v54, s98, s98
	v_fma_f32 v50, v50, s98, s98
	v_exp_f32_e32 v53, v53
	v_rcp_f32_e32 v54, v54
	v_rcp_f32_e32 v50, v50
	v_fma_f32 v55, v55, s98, s98
	v_fma_f32 v51, v51, s98, s98
	v_rcp_f32_e32 v55, v55
	v_rcp_f32_e32 v51, v51
	v_fma_f32 v56, v56, s98, s98
	v_fma_f32 v52, v52, s98, s98
	v_rcp_f32_e32 v56, v56
	v_rcp_f32_e32 v52, v52
	v_fma_f32 v57, v57, s98, s98
	v_rcp_f32_e32 v57, v57
	v_fma_f32 v53, v53, s98, s98
	v_rcp_f32_e32 v53, v53
	v_cvt_pk_u8_f32 v54, v54, 0, 0
	v_cvt_pk_u8_f32 v50, v50, 0, 0
	v_cvt_pk_u8_f32 v54, v55, 1, v54
	v_cvt_pk_u8_f32 v50, v51, 1, v50
	v_cvt_pk_u8_f32 v51, v56, 2, v54
	v_cvt_pk_u8_f32 v52, v52, 2, v50
	v_readlane_b32 s0, v253, 13
	v_cvt_pk_u8_f32 v50, v57, 3, v51
	v_readlane_b32 s1, v253, 14
	v_cvt_pk_u8_f32 v51, v53, 3, v52
	s_nop 0
	v_mov_b64_e32 v[52:53], s[0:1]
	v_mad_i64_i32 v[52:53], s[0:1], v132, s31, v[52:53]
	v_lshl_add_u64 v[52:53], v[52:53], 0, v[0:1]
	v_add_co_u32_e32 v52, vcc, 0x3000, v52
	s_nop 1
	v_addc_co_u32_e32 v53, vcc, 0, v53, vcc
	flat_store_dwordx2 v[52:53], v[50:51] offset:512

; __device__ __forceinline__ float sigmoidf_(float v) { return __builtin_amdgcn_rcpf(1.f + __expf(-v)); }
; __device__ __forceinline__ u32x2 gate_pack8(f32x4 v0, f32x4 v1) {
;     u32x2 w; unsigned x = 0u, y = 0u;
; #pragma unroll
;     for (int j = 0; j < 4; ++j) { x = __builtin_amdgcn_cvt_pk_u8_f32(v0[j] * 255.f, j, x); y = __builtin_amdgcn_cvt_pk_u8_f32(v1[j] * 255.f, j, y); }
;     w.x = x; w.y = y; return w;
; }
;     __device__ __forceinline__ void operator()(const f32x4 (&acc)[2][2][4][2], const Unit& u, int wr, int wc, int fr, int fq) const {
;     ...
;                 for (int m = 0; m < 4; ++m) { const int row = u.pm * BM + ai * HALF + wr * 64 + m * 16 + fr; f32x4 v0 = acc[ai][bj][m][0] * 0.03125f, v1 = acc[ai][bj][m][1] * 0.03125f;
;                     if (gate) {
; #pragma unroll
;                         for (int j = 0; j < 4; ++j) { v0[j] = sigmoidf_(v0[j] + b0[j]); v1[j] = sigmoidf_(v1[j] + b1[j]); }
;                         *(u32x2*)((unsigned char*)(O_ + (size_t)row * NP + GATE0) + (col - 2048)) = gate_pack8(v0, v1); }
.LBB0_760:
	s_andn2_b64 vcc, exec, s[42:43]
	s_cbranch_vccnz .LBB0_762
	s_waitcnt vmcnt(0)
	v_fma_f32 v46, v46, s101, v70
	v_fma_f32 v42, v42, s101, v66
	v_fma_f32 v47, v47, s101, v71
	v_fma_f32 v43, v43, s101, v67
	v_exp_f32_e32 v46, v46
	v_exp_f32_e32 v42, v42
	v_fma_f32 v48, v48, s101, v72
	v_fma_f32 v44, v44, s101, v68
	v_exp_f32_e32 v47, v47
	v_exp_f32_e32 v43, v43
	v_fma_f32 v49, v49, s101, v73
	v_exp_f32_e32 v48, v48
	v_exp_f32_e32 v44, v44
	v_fma_f32 v45, v45, s101, v69
	v_exp_f32_e32 v49, v49
	v_fma_f32 v46, v46, s98, s98
	v_fma_f32 v42, v42, s98, s98
	v_exp_f32_e32 v45, v45
	v_rcp_f32_e32 v46, v46
	v_rcp_f32_e32 v42, v42
	v_fma_f32 v47, v47, s98, s98
	v_fma_f32 v43, v43, s98, s98
	v_rcp_f32_e32 v47, v47
	v_rcp_f32_e32 v43, v43
	v_fma_f32 v48, v48, s98, s98
	v_fma_f32 v44, v44, s98, s98
	v_rcp_f32_e32 v48, v48
	v_rcp_f32_e32 v44, v44
	v_fma_f32 v49, v49, s98, s98
	v_rcp_f32_e32 v49, v49
	v_fma_f32 v45, v45, s98, s98
	v_rcp_f32_e32 v45, v45
	v_cvt_pk_u8_f32 v46, v46, 0, 0
	v_cvt_pk_u8_f32 v42, v42, 0, 0
	v_cvt_pk_u8_f32 v46, v47, 1, v46
	v_cvt_pk_u8_f32 v42, v43, 1, v42
	v_cvt_pk_u8_f32 v43, v48, 2, v46
	v_cvt_pk_u8_f32 v44, v44, 2, v42
	v_readlane_b32 s0, v253, 13
	v_cvt_pk_u8_f32 v42, v49, 3, v43
	v_readlane_b32 s1, v253, 14
	v_cvt_pk_u8_f32 v43, v45, 3, v44
	s_nop 0
	v_mov_b64_e32 v[44:45], s[0:1]
	v_mad_i64_i32 v[44:45], s[0:1], v122, s31, v[44:45]
	v_lshl_add_u64 v[44:45], v[44:45], 0, v[0:1]
	v_add_co_u32_e32 v44, vcc, 0x3000, v44
	s_nop 1
	v_addc_co_u32_e32 v45, vcc, 0, v45, vcc
	flat_store_dwordx2 v[44:45], v[42:43] offset:512

; __device__ __forceinline__ float sigmoidf_(float v) { return __builtin_amdgcn_rcpf(1.f + __expf(-v)); }
; __device__ __forceinline__ u32x2 gate_pack8(f32x4 v0, f32x4 v1) {
;     u32x2 w; unsigned x = 0u, y = 0u;
; #pragma unroll
;     for (int j = 0; j < 4; ++j) { x = __builtin_amdgcn_cvt_pk_u8_f32(v0[j] * 255.f, j, x); y = __builtin_amdgcn_cvt_pk_u8_f32(v1[j] * 255.f, j, y); }
;     w.x = x; w.y = y; return w;
; }
;     __device__ __forceinline__ void operator()(const f32x4 (&acc)[2][2][4][2], const Unit& u, int wr, int wc, int fr, int fq) const {
;     ...
;                 for (int m = 0; m < 4; ++m) { const int row = u.pm * BM + ai * HALF + wr * 64 + m * 16 + fr; f32x4 v0 = acc[ai][bj][m][0] * 0.03125f, v1 = acc[ai][bj][m][1] * 0.03125f;
;                     if (gate) {
; #pragma unroll
;                         for (int j = 0; j < 4; ++j) { v0[j] = sigmoidf_(v0[j] + b0[j]); v1[j] = sigmoidf_(v1[j] + b1[j]); }
;                         *(u32x2*)((unsigned char*)(O_ + (size_t)row * NP + GATE0) + (col - 2048)) = gate_pack8(v0, v1); }
.LBB0_764:
	s_andn2_b64 vcc, exec, s[42:43]
	s_cbranch_vccnz .LBB0_766
	s_waitcnt vmcnt(0)
	v_fma_f32 v38, v38, s101, v70
	v_fma_f32 v34, v34, s101, v66
	v_fma_f32 v39, v39, s101, v71
	v_fma_f32 v35, v35, s101, v67
	v_exp_f32_e32 v38, v38
	v_exp_f32_e32 v34, v34
	v_fma_f32 v40, v40, s101, v72
	v_fma_f32 v36, v36, s101, v68
	v_exp_f32_e32 v39, v39
	v_exp_f32_e32 v35, v35
	v_fma_f32 v41, v41, s101, v73
	v_exp_f32_e32 v40, v40
	v_exp_f32_e32 v36, v36
	v_fma_f32 v37, v37, s101, v69
	v_exp_f32_e32 v41, v41
	v_fma_f32 v38, v38, s98, s98
	v_fma_f32 v34, v34, s98, s98
	v_exp_f32_e32 v37, v37
	v_rcp_f32_e32 v38, v38
	v_rcp_f32_e32 v34, v34
	v_fma_f32 v39, v39, s98, s98
	v_fma_f32 v35, v35, s98, s98
	v_rcp_f32_e32 v39, v39
	v_rcp_f32_e32 v35, v35
	v_fma_f32 v40, v40, s98, s98
	v_fma_f32 v36, v36, s98, s98
	v_rcp_f32_e32 v40, v40
	v_rcp_f32_e32 v36, v36
	v_fma_f32 v41, v41, s98, s98
	v_rcp_f32_e32 v41, v41
	v_fma_f32 v37, v37, s98, s98
	v_rcp_f32_e32 v37, v37
	v_cvt_pk_u8_f32 v38, v38, 0, 0
	v_cvt_pk_u8_f32 v34, v34, 0, 0
	v_cvt_pk_u8_f32 v38, v39, 1, v38
	v_cvt_pk_u8_f32 v34, v35, 1, v34
	v_cvt_pk_u8_f32 v35, v40, 2, v38
	v_cvt_pk_u8_f32 v36, v36, 2, v34
	v_readlane_b32 s0, v253, 13
	v_cvt_pk_u8_f32 v34, v41, 3, v35
	v_readlane_b32 s1, v253, 14
	v_cvt_pk_u8_f32 v35, v37, 3, v36
	s_nop 0
	v_mov_b64_e32 v[36:37], s[0:1]
	v_mad_i64_i32 v[36:37], s[0:1], v106, s31, v[36:37]
	v_lshl_add_u64 v[36:37], v[36:37], 0, v[0:1]
	v_add_co_u32_e32 v36, vcc, 0x3000, v36
	s_nop 1
	v_addc_co_u32_e32 v37, vcc, 0, v37, vcc
	flat_store_dwordx2 v[36:37], v[34:35] offset:512

; __device__ __forceinline__ float sigmoidf_(float v) { return __builtin_amdgcn_rcpf(1.f + __expf(-v)); }
; __device__ __forceinline__ u32x2 gate_pack8(f32x4 v0, f32x4 v1) {
;     u32x2 w; unsigned x = 0u, y = 0u;
; #pragma unroll
;     for (int j = 0; j < 4; ++j) { x = __builtin_amdgcn_cvt_pk_u8_f32(v0[j] * 255.f, j, x); y = __builtin_amdgcn_cvt_pk_u8_f32(v1[j] * 255.f, j, y); }
;     w.x = x; w.y = y; return w;
; }
;     __device__ __forceinline__ void operator()(const f32x4 (&acc)[2][2][4][2], const Unit& u, int wr, int wc, int fr, int fq) const {
;     ...
;                 for (int m = 0; m < 4; ++m) { const int row = u.pm * BM + ai * HALF + wr * 64 + m * 16 + fr; f32x4 v0 = acc[ai][bj][m][0] * 0.03125f, v1 = acc[ai][bj][m][1] * 0.03125f;
;                     if (gate) {
; #pragma unroll
;                         for (int j = 0; j < 4; ++j) { v0[j] = sigmoidf_(v0[j] + b0[j]); v1[j] = sigmoidf_(v1[j] + b1[j]); }
;                         *(u32x2*)((unsigned char*)(O_ + (size_t)row * NP + GATE0) + (col - 2048)) = gate_pack8(v0, v1); }
.LBB0_768:
	s_andn2_b64 vcc, exec, s[42:43]
	s_cbranch_vccnz .LBB0_770
	s_waitcnt vmcnt(0)
	v_fma_f32 v30, v30, s101, v70
	v_fma_f32 v26, v26, s101, v66
	v_fma_f32 v31, v31, s101, v71
	v_fma_f32 v27, v27, s101, v67
	v_exp_f32_e32 v30, v30
	v_exp_f32_e32 v26, v26
	v_fma_f32 v32, v32, s101, v72
	v_fma_f32 v28, v28, s101, v68
	v_exp_f32_e32 v31, v31
	v_exp_f32_e32 v27, v27
	v_fma_f32 v33, v33, s101, v73
	v_exp_f32_e32 v32, v32
	v_exp_f32_e32 v28, v28
	v_fma_f32 v29, v29, s101, v69
	v_exp_f32_e32 v33, v33
	v_fma_f32 v30, v30, s98, s98
	v_fma_f32 v26, v26, s98, s98
	v_exp_f32_e32 v29, v29
	v_rcp_f32_e32 v30, v30
	v_rcp_f32_e32 v26, v26
	v_fma_f32 v31, v31, s98, s98
	v_fma_f32 v27, v27, s98, s98
	v_rcp_f32_e32 v31, v31
	v_rcp_f32_e32 v27, v27
	v_fma_f32 v32, v32, s98, s98
	v_fma_f32 v28, v28, s98, s98
	v_rcp_f32_e32 v32, v32
	v_rcp_f32_e32 v28, v28
	v_fma_f32 v33, v33, s98, s98
	v_rcp_f32_e32 v33, v33
	v_fma_f32 v29, v29, s98, s98
	v_rcp_f32_e32 v29, v29
	v_cvt_pk_u8_f32 v30, v30, 0, 0
	v_cvt_pk_u8_f32 v26, v26, 0, 0
	v_cvt_pk_u8_f32 v30, v31, 1, v30
	v_cvt_pk_u8_f32 v26, v27, 1, v26
	v_cvt_pk_u8_f32 v27, v32, 2, v30
	v_cvt_pk_u8_f32 v28, v28, 2, v26
	v_readlane_b32 s0, v253, 13
	v_cvt_pk_u8_f32 v26, v33, 3, v27
	v_readlane_b32 s1, v253, 14
	v_cvt_pk_u8_f32 v27, v29, 3, v28
	s_nop 0
	v_mov_b64_e32 v[28:29], s[0:1]
	v_mad_i64_i32 v[28:29], s[0:1], v98, s31, v[28:29]
	v_lshl_add_u64 v[28:29], v[28:29], 0, v[0:1]
	v_add_co_u32_e32 v28, vcc, 0x3000, v28
	s_nop 1
	v_addc_co_u32_e32 v29, vcc, 0, v29, vcc
	flat_store_dwordx2 v[28:29], v[26:27] offset:512

; __device__ __forceinline__ float sigmoidf_(float v) { return __builtin_amdgcn_rcpf(1.f + __expf(-v)); }
; __device__ __forceinline__ u32x2 gate_pack8(f32x4 v0, f32x4 v1) {
;     u32x2 w; unsigned x = 0u, y = 0u;
; #pragma unroll
;     for (int j = 0; j < 4; ++j) { x = __builtin_amdgcn_cvt_pk_u8_f32(v0[j] * 255.f, j, x); y = __builtin_amdgcn_cvt_pk_u8_f32(v1[j] * 255.f, j, y); }
;     w.x = x; w.y = y; return w;
; }
;     __device__ __forceinline__ void operator()(const f32x4 (&acc)[2][2][4][2], const Unit& u, int wr, int wc, int fr, int fq) const {
;     ...
;                 for (int m = 0; m < 4; ++m) { const int row = u.pm * BM + ai * HALF + wr * 64 + m * 16 + fr; f32x4 v0 = acc[ai][bj][m][0] * 0.03125f, v1 = acc[ai][bj][m][1] * 0.03125f;
;                     if (gate) {
; #pragma unroll
;                         for (int j = 0; j < 4; ++j) { v0[j] = sigmoidf_(v0[j] + b0[j]); v1[j] = sigmoidf_(v1[j] + b1[j]); }
;                         *(u32x2*)((unsigned char*)(O_ + (size_t)row * NP + GATE0) + (col - 2048)) = gate_pack8(v0, v1); }
.LBB0_772:
	s_andn2_b64 vcc, exec, s[42:43]
	s_cbranch_vccnz .LBB0_774
	s_waitcnt vmcnt(0)
	v_fma_f32 v22, v22, s101, v70
	v_fma_f32 v18, v18, s101, v66
	v_fma_f32 v23, v23, s101, v71
	v_fma_f32 v19, v19, s101, v67
	v_exp_f32_e32 v22, v22
	v_exp_f32_e32 v18, v18
	v_fma_f32 v24, v24, s101, v72
	v_fma_f32 v20, v20, s101, v68
	v_exp_f32_e32 v23, v23
	v_exp_f32_e32 v19, v19
	v_fma_f32 v25, v25, s101, v73
	v_exp_f32_e32 v24, v24
	v_exp_f32_e32 v20, v20
	v_fma_f32 v21, v21, s101, v69
	v_exp_f32_e32 v25, v25
	v_fma_f32 v22, v22, s98, s98
	v_fma_f32 v18, v18, s98, s98
	v_exp_f32_e32 v21, v21
	v_rcp_f32_e32 v22, v22
	v_rcp_f32_e32 v18, v18
	v_fma_f32 v23, v23, s98, s98
	v_fma_f32 v19, v19, s98, s98
	v_rcp_f32_e32 v23, v23
	v_rcp_f32_e32 v19, v19
	v_fma_f32 v24, v24, s98, s98
	v_fma_f32 v20, v20, s98, s98
	v_rcp_f32_e32 v24, v24
	v_rcp_f32_e32 v20, v20
	v_fma_f32 v25, v25, s98, s98
	v_rcp_f32_e32 v25, v25
	v_fma_f32 v21, v21, s98, s98
	v_rcp_f32_e32 v21, v21
	v_cvt_pk_u8_f32 v22, v22, 0, 0
	v_cvt_pk_u8_f32 v18, v18, 0, 0
	v_cvt_pk_u8_f32 v22, v23, 1, v22
	v_cvt_pk_u8_f32 v18, v19, 1, v18
	v_cvt_pk_u8_f32 v19, v24, 2, v22
	v_cvt_pk_u8_f32 v20, v20, 2, v18
	v_readlane_b32 s0, v253, 13
	v_cvt_pk_u8_f32 v18, v25, 3, v19
	v_readlane_b32 s1, v253, 14
	v_cvt_pk_u8_f32 v19, v21, 3, v20
	s_nop 0
	v_mov_b64_e32 v[20:21], s[0:1]
	v_mad_i64_i32 v[20:21], s[0:1], v90, s31, v[20:21]
	v_lshl_add_u64 v[20:21], v[20:21], 0, v[0:1]
	v_add_co_u32_e32 v20, vcc, 0x3000, v20
	s_nop 1
	v_addc_co_u32_e32 v21, vcc, 0, v21, vcc
	flat_store_dwordx2 v[20:21], v[18:19] offset:512

; __device__ __forceinline__ float sigmoidf_(float v) { return __builtin_amdgcn_rcpf(1.f + __expf(-v)); }
; __device__ __forceinline__ u32x2 gate_pack8(f32x4 v0, f32x4 v1) {
;     u32x2 w; unsigned x = 0u, y = 0u;
; #pragma unroll
;     for (int j = 0; j < 4; ++j) { x = __builtin_amdgcn_cvt_pk_u8_f32(v0[j] * 255.f, j, x); y = __builtin_amdgcn_cvt_pk_u8_f32(v1[j] * 255.f, j, y); }
;     w.x = x; w.y = y; return w;
; }
;     __device__ __forceinline__ void operator()(const f32x4 (&acc)[2][2][4][2], const Unit& u, int wr, int wc, int fr, int fq) const {
;     ...
;                 for (int m = 0; m < 4; ++m) { const int row = u.pm * BM + ai * HALF + wr * 64 + m * 16 + fr; f32x4 v0 = acc[ai][bj][m][0] * 0.03125f, v1 = acc[ai][bj][m][1] * 0.03125f;
;                     if (gate) {
; #pragma unroll
;                         for (int j = 0; j < 4; ++j) { v0[j] = sigmoidf_(v0[j] + b0[j]); v1[j] = sigmoidf_(v1[j] + b1[j]); }
;                         *(u32x2*)((unsigned char*)(O_ + (size_t)row * NP + GATE0) + (col - 2048)) = gate_pack8(v0, v1); }
.LBB0_776:
	s_andn2_b64 vcc, exec, s[42:43]
	s_cbranch_vccnz .LBB0_778
	s_waitcnt vmcnt(0)
	v_fma_f32 v14, v14, s101, v70
	v_fma_f32 v10, v10, s101, v66
	v_fma_f32 v15, v15, s101, v71
	v_fma_f32 v11, v11, s101, v67
	v_exp_f32_e32 v14, v14
	v_exp_f32_e32 v10, v10
	v_fma_f32 v16, v16, s101, v72
	v_fma_f32 v12, v12, s101, v68
	v_exp_f32_e32 v15, v15
	v_exp_f32_e32 v11, v11
	v_fma_f32 v17, v17, s101, v73
	v_exp_f32_e32 v16, v16
	v_exp_f32_e32 v12, v12
	v_fma_f32 v13, v13, s101, v69
	v_exp_f32_e32 v17, v17
	v_fma_f32 v14, v14, s98, s98
	v_fma_f32 v10, v10, s98, s98
	v_exp_f32_e32 v13, v13
	v_rcp_f32_e32 v14, v14
	v_rcp_f32_e32 v10, v10
	v_fma_f32 v15, v15, s98, s98
	v_fma_f32 v11, v11, s98, s98
	v_rcp_f32_e32 v15, v15
	v_rcp_f32_e32 v11, v11
	v_fma_f32 v16, v16, s98, s98
	v_fma_f32 v12, v12, s98, s98
	v_rcp_f32_e32 v16, v16
	v_rcp_f32_e32 v12, v12
	v_fma_f32 v17, v17, s98, s98
	v_rcp_f32_e32 v17, v17
	v_fma_f32 v13, v13, s98, s98
	v_rcp_f32_e32 v13, v13
	v_cvt_pk_u8_f32 v14, v14, 0, 0
	v_cvt_pk_u8_f32 v10, v10, 0, 0
	v_cvt_pk_u8_f32 v14, v15, 1, v14
	v_cvt_pk_u8_f32 v10, v11, 1, v10
	v_cvt_pk_u8_f32 v11, v16, 2, v14
	v_cvt_pk_u8_f32 v12, v12, 2, v10
	v_readlane_b32 s0, v253, 13
	v_cvt_pk_u8_f32 v10, v17, 3, v11
	v_readlane_b32 s1, v253, 14
	v_cvt_pk_u8_f32 v11, v13, 3, v12
	s_nop 0
	v_mov_b64_e32 v[12:13], s[0:1]
	v_mad_i64_i32 v[12:13], s[0:1], v82, s31, v[12:13]
	v_lshl_add_u64 v[12:13], v[12:13], 0, v[0:1]
	v_add_co_u32_e32 v12, vcc, 0x3000, v12
	s_nop 1
	v_addc_co_u32_e32 v13, vcc, 0, v13, vcc
	flat_store_dwordx2 v[12:13], v[10:11] offset:512

; __device__ __forceinline__ float sigmoidf_(float v) { return __builtin_amdgcn_rcpf(1.f + __expf(-v)); }
; __device__ __forceinline__ u32x2 gate_pack8(f32x4 v0, f32x4 v1) {
;     u32x2 w; unsigned x = 0u, y = 0u;
; #pragma unroll
;     for (int j = 0; j < 4; ++j) { x = __builtin_amdgcn_cvt_pk_u8_f32(v0[j] * 255.f, j, x); y = __builtin_amdgcn_cvt_pk_u8_f32(v1[j] * 255.f, j, y); }
;     w.x = x; w.y = y; return w;
; }
;     __device__ __forceinline__ void operator()(const f32x4 (&acc)[2][2][4][2], const Unit& u, int wr, int wc, int fr, int fq) const {
;     ...
;                 for (int m = 0; m < 4; ++m) { const int row = u.pm * BM + ai * HALF + wr * 64 + m * 16 + fr; f32x4 v0 = acc[ai][bj][m][0] * 0.03125f, v1 = acc[ai][bj][m][1] * 0.03125f;
;                     if (gate) {
; #pragma unroll
;                         for (int j = 0; j < 4; ++j) { v0[j] = sigmoidf_(v0[j] + b0[j]); v1[j] = sigmoidf_(v1[j] + b1[j]); }
;                         *(u32x2*)((unsigned char*)(O_ + (size_t)row * NP + GATE0) + (col - 2048)) = gate_pack8(v0, v1); }
.LBB0_782:
	s_waitcnt vmcnt(0)
	v_fma_f32 v6, v6, s101, v70
	v_fma_f32 v2, v2, s101, v66
	v_fma_f32 v7, v7, s101, v71
	v_fma_f32 v3, v3, s101, v67
	v_exp_f32_e32 v6, v6
	v_exp_f32_e32 v2, v2
	v_fma_f32 v8, v8, s101, v72
	v_fma_f32 v4, v4, s101, v68
	v_exp_f32_e32 v7, v7
	v_exp_f32_e32 v3, v3
	v_fma_f32 v9, v9, s101, v73
	v_exp_f32_e32 v8, v8
	v_exp_f32_e32 v4, v4
	v_fma_f32 v5, v5, s101, v69
	v_exp_f32_e32 v9, v9
	v_fma_f32 v6, v6, s98, s98
	v_fma_f32 v2, v2, s98, s98
	v_exp_f32_e32 v5, v5
	v_rcp_f32_e32 v6, v6
	v_rcp_f32_e32 v2, v2
	v_fma_f32 v7, v7, s98, s98
	v_fma_f32 v3, v3, s98, s98
	v_rcp_f32_e32 v7, v7
	v_rcp_f32_e32 v3, v3
	v_fma_f32 v8, v8, s98, s98
	v_fma_f32 v4, v4, s98, s98
	v_rcp_f32_e32 v8, v8
	v_rcp_f32_e32 v4, v4
	v_fma_f32 v9, v9, s98, s98
	v_rcp_f32_e32 v9, v9
	v_fma_f32 v5, v5, s98, s98
	v_rcp_f32_e32 v5, v5
	v_cvt_pk_u8_f32 v6, v6, 0, 0
	v_cvt_pk_u8_f32 v2, v2, 0, 0
	v_cvt_pk_u8_f32 v6, v7, 1, v6
	v_cvt_pk_u8_f32 v2, v3, 1, v2
	v_cvt_pk_u8_f32 v3, v8, 2, v6
	v_cvt_pk_u8_f32 v4, v4, 2, v2
	v_readlane_b32 s0, v253, 13
	v_cvt_pk_u8_f32 v2, v9, 3, v3
	v_readlane_b32 s1, v253, 14
	v_cvt_pk_u8_f32 v3, v5, 3, v4
	s_nop 0
	v_mov_b64_e32 v[4:5], s[0:1]
	v_mad_i64_i32 v[4:5], s[0:1], v76, s31, v[4:5]
	v_lshl_add_u64 v[4:5], v[4:5], 0, v[0:1]
	v_add_co_u32_e32 v4, vcc, 0x3000, v4
	s_nop 1
	v_addc_co_u32_e32 v5, vcc, 0, v5, vcc
	flat_store_dwordx2 v[4:5], v[2:3] offset:512
	s_andn2_b64 vcc, exec, s[84:85]
	s_mov_b64 s[40:41], -1
	s_cbranch_vccnz .LBB0_686
